# decode_finish: component-1 partial-record loads issued right behind component 0's (same bases, offset +2112), counted waits raised/recounted: one dependent round trip fewer before the output-projectio
# speedup vs baseline: 1.0208x; 1.0168x over previous
.LBB0_651:
	s_ashr_i32 s45, s75, 2
	s_and_b32 s22, s45, -4
	s_or_b32 s16, s22, s28
	s_ashr_i32 s17, s16, 31
	s_lshl_b64 s[12:13], s[16:17], 11
	s_add_u32 s12, s14, s12
	s_addc_u32 s13, s15, s13
	s_lshl_b32 s20, s76, 9
	s_add_u32 s52, s12, s20
	s_addc_u32 s53, s13, 0
	s_ashr_i32 s23, s22, 31
	v_lshl_add_u64 v[20:21], v[6:7], 0, s[20:21]
	s_lshl_b64 s[12:13], s[22:23], 11
	v_lshl_add_u64 v[14:15], v[20:21], 0, s[12:13]
	global_load_dword v22, v0, s[52:53]
	global_load_dword v24, v[14:15], off
	s_or_b32 s17, s22, s76
	s_or_b32 s44, s22, 1
	s_or_b32 s48, s22, 2
	s_or_b32 s50, s45, 3
	s_lshl_b32 s54, s17, 3
	s_ashr_i32 s45, s44, 31
	s_ashr_i32 s49, s48, 31
	s_ashr_i32 s51, s50, 31
	s_ashr_i32 s55, s54, 31
	s_lshl_b64 s[22:23], s[44:45], 11
	s_lshl_b64 s[44:45], s[48:49], 11
	s_lshl_b64 s[48:49], s[50:51], 11
	s_lshl_b64 s[50:51], s[54:55], 3
	v_lshl_add_u64 v[12:13], v[10:11], 0, s[20:21]
	s_or_b32 s20, s50, s28
	s_mul_i32 s17, s51, 0x210
	s_mul_hi_u32 s51, s20, 0x210
	s_mulk_i32 s20, 0x210
	s_add_i32 s51, s51, s17
	s_add_u32 s68, s24, s20
	s_addc_u32 s69, s25, s51
	s_or_b32 s56, s54, 1
	s_ashr_i32 s57, s56, 31
	s_lshl_b64 s[66:67], s[56:57], 3
	s_or_b32 s20, s66, s28
	s_mulk_i32 s67, 0x210
	s_mul_hi_u32 s51, s20, 0x210
	s_mulk_i32 s20, 0x210
	s_add_i32 s51, s51, s67
	s_add_u32 s70, s24, s20
	s_addc_u32 s71, s25, s51
	s_or_b32 s56, s54, 2
	s_ashr_i32 s57, s56, 31
	s_lshl_b64 s[56:57], s[56:57], 3
	v_lshl_add_u64 v[16:17], v[20:21], 0, s[22:23]
	s_or_b32 s51, s56, s28
	v_lshl_add_u64 v[18:19], v[20:21], 0, s[44:45]
	v_lshl_add_u64 v[20:21], v[20:21], 0, s[48:49]
	global_load_dword v25, v[16:17], off
	global_load_dword v26, v[18:19], off
	global_load_dword v27, v[20:21], off
	global_load_dword v62, v[20:21], off offset:256
	global_load_dword v63, v[18:19], off offset:256
	global_load_dword v64, v[16:17], off offset:256
	global_load_dword v65, v[14:15], off offset:256
	s_nop 0
	global_load_dwordx2 v[14:15], v1, s[68:69]
	global_load_dwordx2 v[16:17], v1, s[70:71]
	global_load_dword v66, v0, s[52:53] offset:256
	s_mul_i32 s20, s57, 0x210
	s_mul_hi_u32 s52, s51, 0x210
	s_mulk_i32 s51, 0x210
	s_add_i32 s53, s52, s20
	s_add_u32 s52, s24, s51
	s_addc_u32 s53, s25, s53
	s_or_b32 s58, s54, 3
	s_ashr_i32 s59, s58, 31
	s_lshl_b64 s[58:59], s[58:59], 3
	s_or_b32 s51, s58, s28
	s_mul_i32 s57, s59, 0x210
	s_mul_hi_u32 s55, s51, 0x210
	s_mulk_i32 s51, 0x210
	s_add_i32 s55, s55, s57
	s_add_u32 s80, s24, s51
	s_addc_u32 s81, s25, s55
	s_or_b32 s60, s54, 4
	s_ashr_i32 s61, s60, 31
	s_lshl_b64 s[60:61], s[60:61], 3
	s_or_b32 s51, s60, s28
	s_mul_i32 s59, s61, 0x210
	s_mul_hi_u32 s55, s51, 0x210
	s_mulk_i32 s51, 0x210
	s_add_i32 s55, s55, s59
	s_add_u32 s82, s24, s51
	s_addc_u32 s83, s25, s55
	s_or_b32 s62, s54, 5
	s_ashr_i32 s63, s62, 31
	s_lshl_b64 s[62:63], s[62:63], 3
	s_or_b32 s51, s62, s28
	s_mul_hi_u32 s55, s51, 0x210
	s_mul_i32 s61, s63, 0x210
	s_add_i32 s55, s55, s61
	s_mulk_i32 s51, 0x210
	s_add_u32 s84, s24, s51
	s_addc_u32 s85, s25, s55
	s_or_b32 s64, s54, 6
	s_ashr_i32 s65, s64, 31
	s_lshl_b64 s[64:65], s[64:65], 3
	s_or_b32 s51, s64, s28
	s_mul_hi_u32 s55, s51, 0x210
	s_mul_i32 s63, s65, 0x210
	s_add_i32 s55, s55, s63
	s_mulk_i32 s51, 0x210
	s_add_u32 s86, s24, s51
	s_addc_u32 s87, s25, s55
	s_or_b32 s54, s54, 7
	s_ashr_i32 s55, s54, 31
	s_lshl_b64 s[54:55], s[54:55], 3
	s_or_b32 s51, s54, s28
	s_mul_hi_u32 s65, s51, 0x210
	s_mulk_i32 s55, 0x210
	s_add_i32 s65, s65, s55
	s_mulk_i32 s51, 0x210
	global_load_dwordx2 v[18:19], v1, s[52:53]
	global_load_dwordx2 v[20:21], v1, s[80:81]
	global_load_dwordx2 v[38:39], v1, s[82:83]
	global_load_dwordx2 v[40:41], v1, s[84:85]
	s_add_u32 s88, s24, s51
	s_addc_u32 s89, s25, s65
	global_load_dwordx2 v[42:43], v1, s[86:87]
	global_load_dwordx2 v[44:45], v1, s[88:89]
	global_load_dwordx2 v[46:47], v31, s[68:69] offset:16
	global_load_dwordx2 v[48:49], v31, s[70:71] offset:16
	global_load_dwordx2 v[50:51], v31, s[52:53] offset:16
	global_load_dwordx2 v[52:53], v31, s[80:81] offset:16
	global_load_dwordx2 v[54:55], v31, s[82:83] offset:16
	global_load_dwordx2 v[56:57], v31, s[84:85] offset:16
	global_load_dwordx2 v[58:59], v31, s[86:87] offset:16
	global_load_dwordx2 v[60:61], v31, s[88:89] offset:16
	global_load_dwordx2 v[100:101], v1, s[68:69] offset:2112
	global_load_dwordx2 v[102:103], v1, s[70:71] offset:2112
	global_load_dwordx2 v[104:105], v1, s[52:53] offset:2112
	global_load_dwordx2 v[106:107], v1, s[80:81] offset:2112
	global_load_dwordx2 v[108:109], v1, s[82:83] offset:2112
	global_load_dwordx2 v[110:111], v1, s[84:85] offset:2112
	global_load_dwordx2 v[112:113], v1, s[86:87] offset:2112
	global_load_dwordx2 v[114:115], v1, s[88:89] offset:2112
	global_load_dwordx2 v[116:117], v31, s[68:69] offset:2128
	global_load_dwordx2 v[118:119], v31, s[70:71] offset:2128
	global_load_dwordx2 v[120:121], v31, s[52:53] offset:2128
	global_load_dwordx2 v[122:123], v31, s[80:81] offset:2128
	global_load_dwordx2 v[124:125], v31, s[82:83] offset:2128
	global_load_dwordx2 v[126:127], v31, s[84:85] offset:2128
	global_load_dwordx2 v[128:129], v31, s[86:87] offset:2128
	global_load_dwordx2 v[130:131], v31, s[88:89] offset:2128
	s_waitcnt vmcnt(40)
	v_mul_f32_e32 v84, v22, v24
	s_nop 1
	v_mov_b32_dpp v84, v84 quad_perm:[1,0,3,2] row_mask:0xf bank_mask:0xf bound_ctrl:1
	v_fmac_f32_e32 v84, v22, v24
	s_nop 1
	v_add_f32_dpp v84, v84, v84 quad_perm:[2,3,0,1] row_mask:0xf bank_mask:0xf bound_ctrl:1
	s_nop 1
	v_add_f32_dpp v84, v84, v84 row_half_mirror row_mask:0xf bank_mask:0xf bound_ctrl:1
	s_nop 1
	v_add_f32_dpp v84, v84, v84 row_ror:8 row_mask:0xf bank_mask:0xf bound_ctrl:1
	v_mov_b32_e32 v85, v84
	s_nop 1
	v_permlane16_swap_b32_e32 v84, v85
	v_add_f32_e32 v24, v84, v85
	v_mov_b32_e32 v86, v24
	s_nop 1
	v_permlane32_swap_b32_e32 v24, v86
	v_add_f32_e32 v67, v24, v86
	v_mul_f32_e32 v91, v87, v88
	s_nop 1
	v_mov_b32_dpp v91, v91 quad_perm:[1,0,3,2] row_mask:0xf bank_mask:0xf bound_ctrl:1
	v_mul_f32_e32 v92, v89, v90
	v_fmac_f32_e32 v91, v87, v88
	s_nop 1
	v_mov_b32_dpp v92, v92 quad_perm:[1,0,3,2] row_mask:0xf bank_mask:0xf bound_ctrl:1
	v_fmac_f32_e32 v92, v89, v90
	s_nop 1
	v_add_f32_dpp v94, v91, v91 quad_perm:[2,3,0,1] row_mask:0xf bank_mask:0xf bound_ctrl:1
	s_nop 1
	v_add_f32_dpp v95, v92, v92 quad_perm:[2,3,0,1] row_mask:0xf bank_mask:0xf bound_ctrl:1
	s_nop 1
	v_add_f32_dpp v94, v94, v94 row_half_mirror row_mask:0xf bank_mask:0xf bound_ctrl:1
	s_nop 1
	v_add_f32_dpp v95, v95, v95 row_half_mirror row_mask:0xf bank_mask:0xf bound_ctrl:1
	s_nop 1
	v_add_f32_dpp v94, v94, v94 row_ror:8 row_mask:0xf bank_mask:0xf bound_ctrl:1
	v_mov_b32_e32 v96, v94
	s_nop 1
	v_add_f32_dpp v95, v95, v95 row_ror:8 row_mask:0xf bank_mask:0xf bound_ctrl:1
	v_mov_b32_e32 v97, v95
	s_nop 1
	v_permlane16_swap_b32_e32 v94, v96
	s_nop 1
	v_permlane16_swap_b32_e32 v95, v97
	v_add_f32_e32 v91, v94, v96
	v_add_f32_e32 v97, v95, v97
	v_mov_b32_e32 v93, v91
	v_mov_b32_e32 v92, v97
	s_nop 1
	v_permlane32_swap_b32_e32 v91, v93
	s_nop 1
	v_permlane32_swap_b32_e32 v97, v92
	v_add_f32_e32 v91, v91, v93
	v_add_f32_e32 v97, v97, v92
	v_mul_f32_e32 v91, 0x3fb8aa3b, v91
	v_mul_f32_e32 v97, 0x3fb8aa3b, v97
	v_exp_f32_e32 v91, v91
	v_exp_f32_e32 v97, v97
	s_nop 1
	v_sub_f32_e32 v4, v91, v97
	v_add_f32_e32 v4, 0x3e4ccccd, v4
	v_mov_b32_e32 v5, v4
	s_waitcnt vmcnt(39)
	v_mul_f32_e32 v24, v22, v25
	v_fmac_f32_e32 v67, v37, v9
	s_or_b32 s50, s50, s29
	v_mov_b32_dpp v24, v24 quad_perm:[1,0,3,2] row_mask:0xf bank_mask:0xf bound_ctrl:1
	v_fmac_f32_e32 v24, v22, v25
	s_mul_hi_u32 s51, s50, 0x210
	s_add_i32 s51, s51, s17
	v_add_f32_dpp v24, v24, v24 quad_perm:[2,3,0,1] row_mask:0xf bank_mask:0xf bound_ctrl:1
	s_mulk_i32 s50, 0x210
	s_add_u32 s50, s24, s50
	v_add_f32_dpp v24, v24, v24 row_half_mirror row_mask:0xf bank_mask:0xf bound_ctrl:1
	s_addc_u32 s51, s25, s51
	s_or_b32 s17, s66, s29
	v_add_f32_dpp v24, v24, v24 row_ror:8 row_mask:0xf bank_mask:0xf bound_ctrl:1
	v_mov_b32_e32 v25, v24
	s_nop 1
	v_permlane16_swap_b32_e32 v24, v25
	v_add_f32_e32 v24, v24, v25
	v_mov_b32_e32 v25, v24
	s_nop 1
	v_permlane32_swap_b32_e32 v24, v25
	v_add_f32_e32 v24, v24, v25
	v_fmac_f32_e32 v24, v37, v23
	v_cndmask_b32_e64 v68, v24, v30, s[6:7]
	s_waitcnt vmcnt(38)
	v_mul_f32_e32 v24, v22, v26
	s_mul_hi_u32 s52, s17, 0x210
	s_add_i32 s53, s52, s67
	v_mov_b32_dpp v24, v24 quad_perm:[1,0,3,2] row_mask:0xf bank_mask:0xf bound_ctrl:1
	v_fmac_f32_e32 v24, v22, v26
	s_mulk_i32 s17, 0x210
	s_add_u32 s52, s24, s17
	v_add_f32_dpp v24, v24, v24 quad_perm:[2,3,0,1] row_mask:0xf bank_mask:0xf bound_ctrl:1
	s_addc_u32 s53, s25, s53
	s_nop 0
	v_add_f32_dpp v24, v24, v24 row_half_mirror row_mask:0xf bank_mask:0xf bound_ctrl:1
	s_nop 1
	v_add_f32_dpp v24, v24, v24 row_ror:8 row_mask:0xf bank_mask:0xf bound_ctrl:1
	v_mov_b32_e32 v25, v24
	s_nop 1
	v_permlane16_swap_b32_e32 v24, v25
	v_add_f32_e32 v24, v24, v25
	v_mov_b32_e32 v25, v24
	s_nop 1
	v_permlane32_swap_b32_e32 v24, v25
	v_add_f32_e32 v24, v24, v25
	v_fmac_f32_e32 v24, v37, v28
	v_cndmask_b32_e64 v69, v24, v30, s[8:9]
	s_waitcnt vmcnt(37)
	v_mul_f32_e32 v24, v22, v27
	s_nop 1
	v_mov_b32_dpp v24, v24 quad_perm:[1,0,3,2] row_mask:0xf bank_mask:0xf bound_ctrl:1
	v_fmac_f32_e32 v24, v22, v27
	s_nop 1
	v_add_f32_dpp v22, v24, v24 quad_perm:[2,3,0,1] row_mask:0xf bank_mask:0xf bound_ctrl:1
	s_nop 1
	v_add_f32_dpp v22, v22, v22 row_half_mirror row_mask:0xf bank_mask:0xf bound_ctrl:1
	s_nop 1
	v_add_f32_dpp v22, v22, v22 row_ror:8 row_mask:0xf bank_mask:0xf bound_ctrl:1
	v_mov_b32_e32 v24, v22
	s_nop 1
	v_permlane16_swap_b32_e32 v22, v24
	v_add_f32_e32 v22, v22, v24
	v_mov_b32_e32 v24, v22
	s_nop 1
	v_permlane32_swap_b32_e32 v22, v24
	v_add_f32_e32 v22, v22, v24
	v_fmac_f32_e32 v22, v37, v29
	v_cndmask_b32_e64 v70, v30, v22, s[10:11]
	v_max_f32_e32 v22, v67, v68
	v_max3_f32 v22, v22, v69, v70
	s_waitcnt vmcnt(31)
	v_max3_f32 v22, v22, v14, v16
	s_waitcnt vmcnt(28)
	v_max3_f32 v22, v22, v18, v20
	s_waitcnt vmcnt(26)
	v_max3_f32 v22, v22, v38, v40
	s_waitcnt vmcnt(24)
	v_max3_f32 v71, v22, v42, v44
	v_sub_f32_e32 v14, v14, v71
	v_exp_f32_e32 v14, v14
	v_sub_f32_e32 v16, v16, v71
	v_exp_f32_e32 v16, v16
	v_sub_f32_e32 v18, v18, v71
	v_exp_f32_e32 v18, v18
	v_sub_f32_e32 v20, v20, v71
	v_fma_f32 v72, v14, v15, 0
	v_sub_f32_e32 v15, v38, v71
	v_exp_f32_e32 v20, v20
	v_exp_f32_e32 v22, v15
	v_sub_f32_e32 v15, v40, v71
	v_exp_f32_e32 v38, v15
	v_sub_f32_e32 v15, v42, v71
	v_fmac_f32_e32 v72, v16, v17
	v_exp_f32_e32 v40, v15
	v_sub_f32_e32 v15, v44, v71
	v_fmac_f32_e32 v72, v18, v19
	v_exp_f32_e32 v42, v15
	s_waitcnt vmcnt(23)
	v_pk_fma_f32 v[14:15], v[14:15], v[46:47], 0 op_sel_hi:[0,1,0]
	v_fmac_f32_e32 v72, v20, v21
	s_waitcnt vmcnt(22)
	v_pk_fma_f32 v[14:15], v[16:17], v[48:49], v[14:15] op_sel_hi:[0,1,1]
	v_sub_f32_e32 v16, v67, v71
	v_fmac_f32_e32 v72, v22, v39
	v_exp_f32_e32 v16, v16
	v_sub_f32_e32 v17, v68, v71
	v_fmac_f32_e32 v72, v38, v41
	s_waitcnt vmcnt(21)
	v_pk_fma_f32 v[14:15], v[18:19], v[50:51], v[14:15] op_sel_hi:[0,1,1]
	v_exp_f32_e32 v18, v17
	v_sub_f32_e32 v17, v69, v71
	v_fmac_f32_e32 v72, v40, v43
	s_waitcnt vmcnt(20)
	v_pk_fma_f32 v[14:15], v[20:21], v[52:53], v[14:15] op_sel_hi:[0,1,1]
	v_exp_f32_e32 v20, v17
	v_sub_f32_e32 v17, v70, v71
	v_fmac_f32_e32 v72, v42, v45
	s_waitcnt vmcnt(19)
	v_pk_fma_f32 v[14:15], v[22:23], v[54:55], v[14:15] op_sel_hi:[0,1,1]
	v_exp_f32_e32 v22, v17
	v_add_f32_e32 v17, v16, v72
	v_add_f32_e32 v17, v18, v17
	v_add_f32_e32 v17, v20, v17
	v_add_f32_e32 v17, v22, v17
	s_waitcnt vmcnt(18)
	v_pk_fma_f32 v[14:15], v[38:39], v[56:57], v[14:15] op_sel_hi:[0,1,1]
	v_lshl_add_u64 v[38:39], v[12:13], 0, s[12:13]
	v_div_scale_f32 v19, s[12:13], v17, v17, 1.0
	s_or_b32 s12, s56, s29
	s_mul_hi_u32 s13, s12, 0x210
	s_add_i32 s13, s13, s20
	s_mulk_i32 s12, 0x210
	s_add_u32 s12, s24, s12
	s_addc_u32 s13, s25, s13
	s_or_b32 s17, s58, s29
	s_mul_hi_u32 s20, s17, 0x210
	s_add_i32 s20, s20, s57
	s_mulk_i32 s17, 0x210
	s_waitcnt vmcnt(17)
	v_pk_fma_f32 v[14:15], v[40:41], v[58:59], v[14:15] op_sel_hi:[0,1,1]
	v_lshl_add_u64 v[40:41], v[12:13], 0, s[22:23]
	s_add_u32 s22, s24, s17
	s_addc_u32 s23, s25, s20
	s_or_b32 s17, s60, s29
	s_mul_hi_u32 s20, s17, 0x210
	s_add_i32 s20, s20, s59
	s_mulk_i32 s17, 0x210
	s_waitcnt vmcnt(16)
	v_pk_fma_f32 v[14:15], v[42:43], v[60:61], v[14:15] op_sel_hi:[0,1,1]
	v_lshl_add_u64 v[42:43], v[12:13], 0, s[44:45]
	s_add_u32 s44, s24, s17
	s_addc_u32 s45, s25, s20
	s_or_b32 s17, s62, s29
	s_mul_hi_u32 s20, s17, 0x210
	v_rcp_f32_e32 v21, v19
	s_add_i32 s20, s20, s61
	s_mulk_i32 s17, 0x210
	v_lshl_add_u64 v[12:13], v[12:13], 0, s[48:49]
	s_add_u32 s48, s24, s17
	s_addc_u32 s49, s25, s20
	s_or_b32 s17, s64, s29
	s_mul_hi_u32 s20, s17, 0x210
	v_fma_f32 v44, -v19, v21, 1.0
	s_add_i32 s20, s20, s63
	s_mulk_i32 s17, 0x210
	v_fmac_f32_e32 v21, v44, v21
	v_div_scale_f32 v44, vcc, 1.0, v17, 1.0
	s_add_u32 s56, s24, s17
	v_mul_f32_e32 v73, v44, v21
	s_addc_u32 s57, s25, s20
	s_or_b32 s17, s54, s29
	s_nop 0
	s_nop 0
	v_fma_f32 v45, -v19, v73, v44
	v_mul_f32_e32 v56, v66, v65
	s_mul_hi_u32 s20, s17, 0x210
	v_fmac_f32_e32 v73, v45, v21
	s_add_i32 s20, s20, s55
	s_mulk_i32 s17, 0x210
	v_mov_b32_dpp v56, v56 quad_perm:[1,0,3,2] row_mask:0xf bank_mask:0xf bound_ctrl:1
	v_fma_f32 v19, -v19, v73, v44
	s_nop 0
	s_nop 0
	s_nop 0
	s_nop 0
	s_add_u32 s54, s24, s17
	v_fmac_f32_e32 v56, v66, v65
	s_addc_u32 s55, s25, s20
	s_nop 0
	s_nop 0
	v_add_f32_dpp v56, v56, v56 quad_perm:[2,3,0,1] row_mask:0xf bank_mask:0xf bound_ctrl:1
	v_div_fmas_f32 v19, v19, v21, v73
	v_div_fixup_f32 v80, v19, v17, 1.0
	v_add_f32_dpp v56, v56, v56 row_half_mirror row_mask:0xf bank_mask:0xf bound_ctrl:1
	s_nop 1
	v_add_f32_dpp v56, v56, v56 row_ror:8 row_mask:0xf bank_mask:0xf bound_ctrl:1
	v_mov_b32_e32 v57, v56
	s_nop 1
	v_permlane16_swap_b32_e32 v56, v57
	v_add_f32_e32 v56, v56, v57
	v_mov_b32_e32 v57, v56
	s_nop 1
	v_permlane32_swap_b32_e32 v56, v57
	v_add_f32_e32 v72, v56, v57
	v_mul_f32_e32 v56, v66, v64
	v_fmac_f32_e32 v72, v37, v9
	s_nop 0
	v_mov_b32_dpp v56, v56 quad_perm:[1,0,3,2] row_mask:0xf bank_mask:0xf bound_ctrl:1
	v_fmac_f32_e32 v56, v66, v64
	s_nop 1
	v_add_f32_dpp v56, v56, v56 quad_perm:[2,3,0,1] row_mask:0xf bank_mask:0xf bound_ctrl:1
	s_nop 1
	v_add_f32_dpp v56, v56, v56 row_half_mirror row_mask:0xf bank_mask:0xf bound_ctrl:1
	s_nop 1
	v_add_f32_dpp v56, v56, v56 row_ror:8 row_mask:0xf bank_mask:0xf bound_ctrl:1
	v_mov_b32_e32 v57, v56
	s_nop 1
	v_permlane16_swap_b32_e32 v56, v57
	v_add_f32_e32 v56, v56, v57
	v_mov_b32_e32 v57, v56
	s_nop 1
	v_permlane32_swap_b32_e32 v56, v57
	v_add_f32_e32 v56, v56, v57
	v_fmac_f32_e32 v56, v37, v23
	v_cndmask_b32_e64 v74, v56, v30, s[6:7]
	v_mul_f32_e32 v56, v66, v63
	s_nop 1
	v_mov_b32_dpp v56, v56 quad_perm:[1,0,3,2] row_mask:0xf bank_mask:0xf bound_ctrl:1
	v_fmac_f32_e32 v56, v66, v63
	s_nop 1
	v_add_f32_dpp v56, v56, v56 quad_perm:[2,3,0,1] row_mask:0xf bank_mask:0xf bound_ctrl:1
	s_nop 1
	v_add_f32_dpp v56, v56, v56 row_half_mirror row_mask:0xf bank_mask:0xf bound_ctrl:1
	s_nop 1
	v_add_f32_dpp v56, v56, v56 row_ror:8 row_mask:0xf bank_mask:0xf bound_ctrl:1
	v_mov_b32_e32 v57, v56
	s_nop 1
	v_permlane16_swap_b32_e32 v56, v57
	v_add_f32_e32 v56, v56, v57
	v_mov_b32_e32 v57, v56
	s_nop 1
	v_permlane32_swap_b32_e32 v56, v57
	v_add_f32_e32 v56, v56, v57
	v_fmac_f32_e32 v56, v37, v28
	v_cndmask_b32_e64 v75, v56, v30, s[8:9]
	v_mul_f32_e32 v56, v66, v62
	s_nop 1
	v_mov_b32_dpp v56, v56 quad_perm:[1,0,3,2] row_mask:0xf bank_mask:0xf bound_ctrl:1
	v_fmac_f32_e32 v56, v66, v62
	s_nop 1
	v_add_f32_dpp v56, v56, v56 quad_perm:[2,3,0,1] row_mask:0xf bank_mask:0xf bound_ctrl:1
	s_nop 1
	v_add_f32_dpp v56, v56, v56 row_half_mirror row_mask:0xf bank_mask:0xf bound_ctrl:1
	s_nop 1
	v_add_f32_dpp v76, v56, v56 row_ror:8 row_mask:0xf bank_mask:0xf bound_ctrl:1
	global_load_dwordx2 v[38:39], v[38:39], off
	s_nop 0
	global_load_dwordx2 v[40:41], v[40:41], off
	s_nop 0
	global_load_dwordx2 v[42:43], v[42:43], off
	s_nop 0
	global_load_dwordx2 v[12:13], v[12:13], off
	s_nop 0
	s_nop 0
	s_nop 0
	s_nop 0
	s_nop 0
	s_nop 0
	s_nop 0
	s_nop 0
	s_nop 0
	v_mov_b32_e32 v77, v76
	s_nop 1
	v_permlane16_swap_b32_e32 v76, v77
	v_add_f32_e32 v76, v76, v77
	v_mov_b32_e32 v77, v76
	s_nop 1
	v_permlane32_swap_b32_e32 v76, v77
	v_add_f32_e32 v76, v76, v77
	v_fmac_f32_e32 v76, v37, v29
	v_cndmask_b32_e64 v37, v30, v76, s[10:11]
	v_max_f32_e32 v76, v72, v74
	v_max3_f32 v76, v76, v75, v37
	s_waitcnt vmcnt(18)
	v_max3_f32 v76, v76, v100, v102
	s_waitcnt vmcnt(16)
	v_max3_f32 v76, v76, v104, v106
	s_waitcnt vmcnt(14)
	v_max3_f32 v76, v76, v108, v110
	s_waitcnt vmcnt(12)
	v_max3_f32 v77, v76, v112, v114
	v_sub_f32_e32 v24, v100, v77
	v_exp_f32_e32 v24, v24
	v_sub_f32_e32 v26, v102, v77
	v_exp_f32_e32 v26, v26
	v_sub_f32_e32 v44, v104, v77
	v_exp_f32_e32 v44, v44
	v_sub_f32_e32 v46, v106, v77
	v_fma_f32 v25, v24, v101, 0
	v_exp_f32_e32 v46, v46
	v_fmac_f32_e32 v25, v26, v103
	v_sub_f32_e32 v27, v108, v77
	v_exp_f32_e32 v48, v27
	v_sub_f32_e32 v27, v110, v77
	v_exp_f32_e32 v50, v27
	v_sub_f32_e32 v27, v112, v77
	v_fmac_f32_e32 v25, v44, v105
	v_exp_f32_e32 v52, v27
	v_sub_f32_e32 v27, v114, v77
	v_fmac_f32_e32 v25, v46, v107
	v_exp_f32_e32 v54, v27
	v_sub_f32_e32 v27, v72, v77
	v_fmac_f32_e32 v25, v48, v109
	v_exp_f32_e32 v72, v27
	v_sub_f32_e32 v27, v74, v77
	v_fmac_f32_e32 v25, v50, v111
	v_exp_f32_e32 v74, v27
	v_sub_f32_e32 v27, v75, v77
	v_fmac_f32_e32 v25, v52, v113
	v_exp_f32_e32 v76, v27
	v_sub_f32_e32 v27, v37, v77
	v_fmac_f32_e32 v25, v54, v115
	v_exp_f32_e32 v78, v27
	v_add_f32_e32 v25, v72, v25
	v_add_f32_e32 v25, v74, v25
	v_add_f32_e32 v25, v76, v25
	v_add_f32_e32 v25, v78, v25
	v_div_scale_f32 v27, s[12:13], v25, v25, 1.0
	v_rcp_f32_e32 v37, v27
	s_nop 0
	v_fma_f32 v17, -v27, v37, 1.0
	v_fmac_f32_e32 v37, v17, v37
	v_div_scale_f32 v17, vcc, 1.0, v25, 1.0
	v_mul_f32_e32 v19, v17, v37
	v_fma_f32 v21, -v27, v19, v17
	v_fmac_f32_e32 v19, v21, v37
	v_fma_f32 v17, -v27, v19, v17
	v_div_fmas_f32 v17, v17, v37, v19
	v_div_fixup_f32 v82, v17, v25, 1.0
	s_waitcnt vmcnt(3)
	v_pk_fma_f32 v[14:15], v[16:17], v[38:39], v[14:15] op_sel_hi:[0,1,1]
	s_waitcnt vmcnt(2)
	v_pk_fma_f32 v[14:15], v[18:19], v[40:41], v[14:15] op_sel_hi:[0,1,1]
	s_waitcnt vmcnt(1)
	v_pk_fma_f32 v[14:15], v[20:21], v[42:43], v[14:15] op_sel_hi:[0,1,1]
	s_waitcnt vmcnt(0)
	v_pk_fma_f32 v[14:15], v[22:23], v[12:13], v[14:15] op_sel_hi:[0,1,1]
	s_waitcnt vmcnt(0)
	v_pk_fma_f32 v[16:17], v[24:25], v[116:117], 0 op_sel_hi:[0,1,0]
	s_waitcnt vmcnt(0)
	v_pk_fma_f32 v[16:17], v[26:27], v[118:119], v[16:17] op_sel_hi:[0,1,1]
	s_waitcnt vmcnt(0)
	v_pk_fma_f32 v[16:17], v[44:45], v[120:121], v[16:17] op_sel_hi:[0,1,1]
	s_waitcnt vmcnt(0)
	v_pk_fma_f32 v[16:17], v[46:47], v[122:123], v[16:17] op_sel_hi:[0,1,1]
	s_waitcnt vmcnt(0)
	v_pk_fma_f32 v[16:17], v[48:49], v[124:125], v[16:17] op_sel_hi:[0,1,1]
	s_waitcnt vmcnt(0)
	v_pk_fma_f32 v[16:17], v[50:51], v[126:127], v[16:17] op_sel_hi:[0,1,1]
	s_waitcnt vmcnt(0)
	v_pk_fma_f32 v[16:17], v[52:53], v[128:129], v[16:17] op_sel_hi:[0,1,1]
	s_waitcnt vmcnt(0)
	v_pk_fma_f32 v[16:17], v[54:55], v[130:131], v[16:17] op_sel_hi:[0,1,1]
	v_pk_fma_f32 v[16:17], v[72:73], v[38:39], v[16:17] op_sel_hi:[0,1,1]
	v_pk_fma_f32 v[16:17], v[74:75], v[40:41], v[16:17] op_sel_hi:[0,1,1]
	v_pk_fma_f32 v[16:17], v[76:77], v[42:43], v[16:17] op_sel_hi:[0,1,1]
	v_pk_fma_f32 v[12:13], v[78:79], v[12:13], v[16:17] op_sel_hi:[0,1,1]
	v_pk_mul_f32 v[12:13], v[82:83], v[12:13] op_sel_hi:[0,1]
	v_pk_mul_f32 v[12:13], v[4:5], v[12:13]
	s_nop 0
	v_pk_fma_f32 v[12:13], v[80:81], v[14:15], v[12:13] op_sel_hi:[0,1,1] neg_lo:[0,0,1] neg_hi:[0,0,1]
	v_pk_mul_f32 v[14:15], v[12:13], v[12:13]
	s_nop 0
	v_add_f32_e32 v14, v14, v15
	s_nop 1
	v_add_f32_dpp v14, v14, v14 quad_perm:[1,0,3,2] row_mask:0xf bank_mask:0xf bound_ctrl:1
	s_nop 1
	v_add_f32_dpp v14, v14, v14 quad_perm:[2,3,0,1] row_mask:0xf bank_mask:0xf bound_ctrl:1
	s_nop 1
	v_add_f32_dpp v14, v14, v14 row_half_mirror row_mask:0xf bank_mask:0xf bound_ctrl:1
	s_nop 1
	v_add_f32_dpp v14, v14, v14 row_ror:8 row_mask:0xf bank_mask:0xf bound_ctrl:1
	v_mov_b32_e32 v15, v14
	s_nop 1
	v_permlane16_swap_b32_e32 v14, v15
	v_add_f32_e32 v14, v14, v15
	v_mov_b32_e32 v15, v14
	s_nop 1
	v_permlane32_swap_b32_e32 v14, v15
	v_add_f32_e32 v14, v14, v15
	v_fmamk_f32 v14, v14, 0x3c000000, v32
	v_mul_f32_e32 v15, 0x4f800000, v14
	v_cmp_gt_f32_e32 vcc, s30, v14
	s_nop 1
	v_cndmask_b32_e32 v14, v14, v15, vcc
	v_sqrt_f32_e32 v15, v14
	s_nop 0
	v_add_u32_e32 v16, -1, v15
	v_fma_f32 v17, -v16, v15, v14
	v_cmp_ge_f32_e64 s[12:13], 0, v17
	v_add_u32_e32 v17, 1, v15
	s_nop 0
	v_cndmask_b32_e64 v16, v15, v16, s[12:13]
	v_fma_f32 v15, -v17, v15, v14
	v_cmp_lt_f32_e64 s[12:13], 0, v15
	s_nop 1
	v_cndmask_b32_e64 v15, v16, v17, s[12:13]
	v_mul_f32_e32 v16, 0x37800000, v15
	v_cndmask_b32_e32 v15, v15, v16, vcc
	v_cmp_class_f32_e32 vcc, v14, v33
	s_nop 1
	v_cndmask_b32_e32 v14, v15, v14, vcc
	v_div_scale_f32 v15, s[12:13], v14, v14, s31
	v_rcp_f32_e32 v16, v15
	s_add_i32 s12, s16, 0x4000
	s_ashr_i32 s13, s12, 31
	s_lshl_b64 s[12:13], s[12:13], 11
	v_fma_f32 v17, -v15, v16, 1.0
	v_fmac_f32_e32 v16, v17, v16
	v_div_scale_f32 v17, vcc, s31, v14, s31
	v_mul_f32_e32 v18, v17, v16
	v_fma_f32 v19, -v15, v18, v17
	v_fmac_f32_e32 v18, v19, v16
	v_fma_f32 v15, -v15, v18, v17
	v_div_fmas_f32 v15, v15, v16, v18
	v_div_fixup_f32 v14, v15, v14, s31
	v_pk_mul_f32 v[12:13], v[12:13], v[14:15] op_sel_hi:[1,0]
	s_add_u32 s12, s26, s12
	v_pk_mul_f32 v[12:13], v[2:3], v[12:13]
	s_addc_u32 s13, s27, s13
	v_and_b32_sdwa v15, v12, v36 dst_sel:DWORD dst_unused:UNUSED_PAD src0_sel:WORD_1 src1_sel:DWORD
	s_lshl_b32 s16, s76, 8
	v_and_b32_sdwa v14, v13, v36 dst_sel:DWORD dst_unused:UNUSED_PAD src0_sel:WORD_1 src1_sel:DWORD
	v_add3_u32 v12, v12, v15, s41
	s_add_u32 s12, s12, s16
	v_add3_u32 v13, v13, v14, s41
	v_lshrrev_b32_e32 v12, 16, v12
	s_addc_u32 s13, s13, 0
	s_add_i32 s75, s75, s34
	v_and_or_b32 v12, v13, s72, v12
	v_lshlrev_b32_e32 v13, 1, v8
	s_cmpk_gt_i32 s75, 0x1ff
	global_store_dword v13, v12, s[12:13] sc1
	s_cbranch_scc1 .LBB0_657
